# G2 epilogue: gate loads of batches 1-3 issued together with batch 0 (one exposed HBM round trip instead of four)
# baseline (speedup 1.0000x reference)
;     __device__ __forceinline__ void operator()(const Acc& acc, const Unit& u, int wr, int wc, int fr, int fq) const {
;     ...
;                 u32x2 gw[2][2]; u32x4 ps[2][2];
; #pragma unroll
;                 for (int mm = 0; mm < 2; ++mm)
; #pragma unroll
;                     for (int bj = 0; bj < 2; ++bj) {
;                         const int row = row0 + ai * 128 + (2 * mh + mm) * 16, col = u.pn * 256 + bj * 128 + wc * 32 + 8 * fq;
;                         gw[mm][bj] = *(const u32x2*)((const unsigned char*)gates + (size_t)row * NGATE + br * 2048 + col);
;                         if (br > 0 && pcs == 0) ps[mm][bj] = scr[soff + (mm * 2 + bj) * 512];
;                     }
.LBB0_1124:
	global_load_dwordx2 v[172:173], v[42:43], off offset:128
	v_add_u32_e32 v187, 0x20, v170
	v_mov_b64_e32 v[206:207], s[52:53]
	v_mad_i64_i32 v[206:207], s[66:67], v187, s63, v[206:207]
	v_lshl_add_u64 v[206:207], v[206:207], 0, v[160:161]
	global_load_dwordx2 v[190:191], v[206:207], off
	global_load_dwordx2 v[192:193], v[206:207], off offset:128
	v_add_u32_e32 v187, 0x30, v170
	v_mov_b64_e32 v[206:207], s[52:53]
	v_mad_i64_i32 v[206:207], s[66:67], v187, s63, v[206:207]
	v_lshl_add_u64 v[206:207], v[206:207], 0, v[160:161]
	global_load_dwordx2 v[194:195], v[206:207], off
	global_load_dwordx2 v[196:197], v[206:207], off offset:128
	v_add_u32_e32 v187, 0x80, v170
	v_mov_b64_e32 v[206:207], s[52:53]
	v_mad_i64_i32 v[206:207], s[66:67], v187, s63, v[206:207]
	v_lshl_add_u64 v[206:207], v[206:207], 0, v[160:161]
	global_load_dwordx2 v[198:199], v[206:207], off
	global_load_dwordx2 v[200:201], v[206:207], off offset:128
	v_add_u32_e32 v187, 0x90, v170
	v_mov_b64_e32 v[206:207], s[52:53]
	v_mad_i64_i32 v[206:207], s[66:67], v187, s63, v[206:207]
	v_lshl_add_u64 v[206:207], v[206:207], 0, v[160:161]
	global_load_dwordx2 v[202:203], v[206:207], off
	global_load_dwordx2 v[204:205], v[206:207], off offset:128
	v_add_u32_e32 v187, 0xa0, v170
	v_mov_b64_e32 v[206:207], s[52:53]
	v_mad_i64_i32 v[206:207], s[66:67], v187, s63, v[206:207]
	v_lshl_add_u64 v[206:207], v[206:207], 0, v[160:161]
	global_load_dwordx2 v[224:225], v[206:207], off
	global_load_dwordx2 v[226:227], v[206:207], off offset:128
	v_add_u32_e32 v187, 0xb0, v170
	v_mov_b64_e32 v[206:207], s[52:53]
	v_mad_i64_i32 v[206:207], s[66:67], v187, s63, v[206:207]
	v_lshl_add_u64 v[206:207], v[206:207], 0, v[160:161]
	global_load_dwordx2 v[244:245], v[206:207], off
	global_load_dwordx2 v[246:247], v[206:207], off offset:128
	s_and_b64 vcc, exec, s[46:47]
	s_cbranch_vccnz .LBB0_1126
	v_add_u32_e32 v42, 0x600, v0
	v_mov_b32_e32 v43, v1
	v_lshl_add_u64 v[42:43], v[42:43], 4, s[4:5]
	global_load_dwordx4 v[42:45], v[42:43], off

; __device__ __forceinline__ float bf_lo(unsigned w) { return __uint_as_float(w << 16); }
; __device__ __forceinline__ float bf_hi(unsigned w) { return __uint_as_float(w & 0xffff0000u); }
;     __device__ __forceinline__ void operator()(const Acc& acc, const Unit& u, int wr, int wc, int fr, int fq) const {
;     ...
;                 u32x2 gw[2][2]; u32x4 ps[2][2];
; #pragma unroll
;                 for (int mm = 0; mm < 2; ++mm)
; #pragma unroll
;                     for (int bj = 0; bj < 2; ++bj) {
;                         const int row = row0 + ai * 128 + (2 * mh + mm) * 16, col = u.pn * 256 + bj * 128 + wc * 32 + 8 * fq;
;                         gw[mm][bj] = *(const u32x2*)((const unsigned char*)gates + (size_t)row * NGATE + br * 2048 + col);
;                         if (br > 0 && pcs == 0) ps[mm][bj] = scr[soff + (mm * 2 + bj) * 512];
;                     }
; #pragma unroll
;                 for (int mm = 0; mm < 2; ++mm)
; #pragma unroll
;                     for (int bj = 0; bj < 2; ++bj) {
;                         const int m = 2 * mh + mm; const int row = row0 + ai * 128 + m * 16; const int colt = bj * 128 + wc * 32 + 8 * fq, col = u.pn * 256 + colt;
;                         const u32x2 g_ = gw[mm][bj]; const float k255 = 1.0f / 255.0f;
;                         f32x4 v0 = acc[ai][bj][m][0], v1 = acc[ai][bj][m][1];
; #pragma unroll
;                         for (int j = 0; j < 4; ++j) { v0[j] *= (float)((g_.x >> (8 * j)) & 0xffu) * k255; v1[j] *= (float)((g_.y >> (8 * j)) & 0xffu) * k255; }
;                         if (pcs) { float* d = pbase + (size_t)(wr * 64 + fr + ai * 128 + m * 16) * 256 + colt; *(f32x4*)d = v0; *(f32x4*)(d + 4) = v1; }
;                         else {
;                             if (br > 0) { const u32x4 p_ = ps[mm][bj];
;                                 v0[0] += bf_lo(p_.x); v0[1] += bf_hi(p_.x); v0[2] += bf_lo(p_.y); v0[3] += bf_hi(p_.y);
;                                 v1[0] += bf_lo(p_.z); v1[1] += bf_hi(p_.z); v1[2] += bf_lo(p_.w); v1[3] += bf_hi(p_.w); }
.LBB0_1162:
	v_or_b32_e32 v122, 32, v170
	v_mov_b64_e32 v[114:115], s[52:53]
	v_add_u32_e32 v0, 0x800, v0
	v_mad_i64_i32 v[114:115], s[30:31], v122, s63, v[114:115]
	v_lshl_add_u64 v[114:115], v[114:115], 0, v[160:161]
	s_nop 0
	s_and_b64 vcc, exec, s[46:47]
	s_cbranch_vccnz .LBB0_1164
	v_lshl_add_u64 v[78:79], v[0:1], 4, s[4:5]
	global_load_dwordx4 v[78:81], v[78:79], off
.LBB0_1164:
	s_nop 0
	s_nop 0
	s_and_b64 vcc, exec, s[46:47]
	s_cbranch_vccnz .LBB0_1166
	v_add_u32_e32 v66, 0x200, v0
	v_mov_b32_e32 v67, v1
	v_lshl_add_u64 v[66:67], v[66:67], 4, s[4:5]
	global_load_dwordx4 v[66:69], v[66:67], off
.LBB0_1166:
	v_or_b32_e32 v118, 48, v170
	v_mov_b64_e32 v[114:115], s[52:53]
	v_mad_i64_i32 v[114:115], s[30:31], v118, s63, v[114:115]
	v_lshl_add_u64 v[114:115], v[114:115], 0, v[160:161]
	s_nop 0
	s_and_b64 vcc, exec, s[46:47]
	v_add_u32_e32 v116, 0x400, v0
	s_cbranch_vccnz .LBB0_1168
	v_mov_b32_e32 v117, v1
	v_lshl_add_u64 v[54:55], v[116:117], 4, s[4:5]
	global_load_dwordx4 v[54:57], v[54:55], off
.LBB0_1168:
	s_nop 0
	s_nop 0
	s_and_b64 vcc, exec, s[46:47]
	s_cbranch_vccnz .LBB0_1170
	v_add_u32_e32 v42, 0x600, v0
	v_mov_b32_e32 v43, v1
	v_lshl_add_u64 v[42:43], v[42:43], 4, s[4:5]
	global_load_dwordx4 v[42:45], v[42:43], off
.LBB0_1170:
	s_waitcnt vmcnt(3)
	v_cvt_f32_ubyte1_e32 v131, v190
	v_cvt_f32_ubyte0_e32 v130, v190
	v_pk_mul_f32 v[130:131], v[130:131], s[62:63] op_sel_hi:[1,0]
	v_or_b32_e32 v126, 32, v168
	v_pk_mul_f32 v[110:111], v[110:111], v[130:131]
	v_cvt_f32_ubyte1_e32 v131, v191
	v_cvt_f32_ubyte0_e32 v130, v191
	v_pk_mul_f32 v[130:131], v[130:131], s[62:63] op_sel_hi:[1,0]
	v_ashrrev_i32_e32 v127, 31, v126
	v_pk_mul_f32 v[106:107], v[106:107], v[130:131]
	v_cvt_f32_ubyte3_e32 v131, v190
	v_cvt_f32_ubyte2_e32 v130, v190
	v_pk_mul_f32 v[130:131], v[130:131], s[62:63] op_sel_hi:[1,0]
	v_lshlrev_b64 v[126:127], 10, v[126:127]
	v_pk_mul_f32 v[112:113], v[112:113], v[130:131]
	v_cvt_f32_ubyte3_e32 v131, v191
	v_cvt_f32_ubyte2_e32 v130, v191
	v_pk_mul_f32 v[128:129], v[130:131], s[62:63] op_sel_hi:[1,0]
	v_lshl_add_u64 v[126:127], s[50:51], 0, v[126:127]
	v_pk_mul_f32 v[108:109], v[108:109], v[128:129]
	s_and_b64 vcc, exec, s[42:43]
	s_mov_b64 s[30:31], -1
	s_cbranch_vccnz .LBB0_1172
	v_mov_b32_e32 v167, v1
	v_lshl_add_u64 v[128:129], v[126:127], 0, v[166:167]
	s_mov_b64 s[30:31], 0
	global_store_dwordx4 v[128:129], v[110:113], off
	global_store_dwordx4 v[128:129], v[106:109], off offset:16

;     __device__ __forceinline__ void operator()(const Acc& acc, const Unit& u, int wr, int wc, int fr, int fq) const {
;     ...
;                         const u32x2 g_ = gw[mm][bj]; const float k255 = 1.0f / 255.0f;
;                         f32x4 v0 = acc[ai][bj][m][0], v1 = acc[ai][bj][m][1];
; #pragma unroll
;                         for (int j = 0; j < 4; ++j) { v0[j] *= (float)((g_.x >> (8 * j)) & 0xffu) * k255; v1[j] *= (float)((g_.y >> (8 * j)) & 0xffu) * k255; }
;                         if (pcs) { float* d = pbase + (size_t)(wr * 64 + fr + ai * 128 + m * 16) * 256 + colt; *(f32x4*)d = v0; *(f32x4*)(d + 4) = v1; }
.LBB0_1179:
	s_waitcnt vmcnt(2)
	v_cvt_f32_ubyte1_e32 v107, v192
	v_cvt_f32_ubyte0_e32 v106, v192
	v_pk_mul_f32 v[106:107], v[106:107], s[62:63] op_sel_hi:[1,0]
	s_and_b64 vcc, exec, s[42:43]
	v_pk_mul_f32 v[102:103], v[102:103], v[106:107]
	v_cvt_f32_ubyte1_e32 v107, v193
	v_cvt_f32_ubyte0_e32 v106, v193
	v_pk_mul_f32 v[106:107], v[106:107], s[62:63] op_sel_hi:[1,0]
	s_mov_b64 s[30:31], -1
	v_pk_mul_f32 v[98:99], v[98:99], v[106:107]
	v_cvt_f32_ubyte3_e32 v107, v192
	v_cvt_f32_ubyte2_e32 v106, v192
	v_pk_mul_f32 v[106:107], v[106:107], s[62:63] op_sel_hi:[1,0]
	s_nop 0
	v_pk_mul_f32 v[104:105], v[104:105], v[106:107]
	v_cvt_f32_ubyte3_e32 v107, v193
	v_cvt_f32_ubyte2_e32 v106, v193
	v_pk_mul_f32 v[106:107], v[106:107], s[62:63] op_sel_hi:[1,0]
	s_nop 0
	v_pk_mul_f32 v[100:101], v[100:101], v[106:107]
	s_cbranch_vccnz .LBB0_1181
	v_mov_b32_e32 v167, v1
	v_lshl_add_u64 v[106:107], v[126:127], 0, v[166:167]
	s_mov_b64 s[30:31], 0
	global_store_dwordx4 v[106:107], v[102:105], off offset:512
	global_store_dwordx4 v[106:107], v[98:101], off offset:528

;     __device__ __forceinline__ void operator()(const Acc& acc, const Unit& u, int wr, int wc, int fr, int fq) const {
;     ...
;                         const int m = 2 * mh + mm; const int row = row0 + ai * 128 + m * 16; const int colt = bj * 128 + wc * 32 + 8 * fq, col = u.pn * 256 + colt;
;                         const u32x2 g_ = gw[mm][bj]; const float k255 = 1.0f / 255.0f;
;                         f32x4 v0 = acc[ai][bj][m][0], v1 = acc[ai][bj][m][1];
; #pragma unroll
;                         for (int j = 0; j < 4; ++j) { v0[j] *= (float)((g_.x >> (8 * j)) & 0xffu) * k255; v1[j] *= (float)((g_.y >> (8 * j)) & 0xffu) * k255; }
;                         if (pcs) { float* d = pbase + (size_t)(wr * 64 + fr + ai * 128 + m * 16) * 256 + colt; *(f32x4*)d = v0; *(f32x4*)(d + 4) = v1; }
.LBB0_1188:
	v_or_b32_e32 v98, 48, v168
	v_ashrrev_i32_e32 v99, 31, v98
	v_lshlrev_b64 v[98:99], 10, v[98:99]
	v_lshl_add_u64 v[100:101], s[50:51], 0, v[98:99]
	s_waitcnt vmcnt(1)
	v_cvt_f32_ubyte1_e32 v99, v194
	v_cvt_f32_ubyte0_e32 v98, v194
	v_pk_mul_f32 v[98:99], v[98:99], s[62:63] op_sel_hi:[1,0]
	s_and_b64 vcc, exec, s[42:43]
	v_pk_mul_f32 v[94:95], v[94:95], v[98:99]
	v_cvt_f32_ubyte1_e32 v99, v195
	v_cvt_f32_ubyte0_e32 v98, v195
	v_pk_mul_f32 v[98:99], v[98:99], s[62:63] op_sel_hi:[1,0]
	s_mov_b64 s[30:31], -1
	v_pk_mul_f32 v[90:91], v[90:91], v[98:99]
	v_cvt_f32_ubyte3_e32 v99, v194
	v_cvt_f32_ubyte2_e32 v98, v194
	v_pk_mul_f32 v[98:99], v[98:99], s[62:63] op_sel_hi:[1,0]
	s_nop 0
	v_pk_mul_f32 v[96:97], v[96:97], v[98:99]
	v_cvt_f32_ubyte3_e32 v99, v195
	v_cvt_f32_ubyte2_e32 v98, v195
	v_pk_mul_f32 v[98:99], v[98:99], s[62:63] op_sel_hi:[1,0]
	s_nop 0
	v_pk_mul_f32 v[92:93], v[92:93], v[98:99]
	s_cbranch_vccnz .LBB0_1190
	v_mov_b32_e32 v167, v1
	v_lshl_add_u64 v[98:99], v[100:101], 0, v[166:167]
	s_mov_b64 s[30:31], 0
	global_store_dwordx4 v[98:99], v[94:97], off
	global_store_dwordx4 v[98:99], v[90:93], off offset:16

;     __device__ __forceinline__ void operator()(const Acc& acc, const Unit& u, int wr, int wc, int fr, int fq) const {
;     ...
;                         const u32x2 g_ = gw[mm][bj]; const float k255 = 1.0f / 255.0f;
;                         f32x4 v0 = acc[ai][bj][m][0], v1 = acc[ai][bj][m][1];
; #pragma unroll
;                         for (int j = 0; j < 4; ++j) { v0[j] *= (float)((g_.x >> (8 * j)) & 0xffu) * k255; v1[j] *= (float)((g_.y >> (8 * j)) & 0xffu) * k255; }
;                         if (pcs) { float* d = pbase + (size_t)(wr * 64 + fr + ai * 128 + m * 16) * 256 + colt; *(f32x4*)d = v0; *(f32x4*)(d + 4) = v1; }
.LBB0_1197:
	s_waitcnt vmcnt(0)
	v_cvt_f32_ubyte1_e32 v91, v196
	v_cvt_f32_ubyte0_e32 v90, v196
	v_pk_mul_f32 v[90:91], v[90:91], s[62:63] op_sel_hi:[1,0]
	s_and_b64 vcc, exec, s[42:43]
	v_pk_mul_f32 v[86:87], v[86:87], v[90:91]
	v_cvt_f32_ubyte1_e32 v91, v197
	v_cvt_f32_ubyte0_e32 v90, v197
	v_pk_mul_f32 v[90:91], v[90:91], s[62:63] op_sel_hi:[1,0]
	s_mov_b64 s[30:31], -1
	v_pk_mul_f32 v[82:83], v[82:83], v[90:91]
	v_cvt_f32_ubyte3_e32 v91, v196
	v_cvt_f32_ubyte2_e32 v90, v196
	v_pk_mul_f32 v[90:91], v[90:91], s[62:63] op_sel_hi:[1,0]
	s_nop 0
	v_pk_mul_f32 v[88:89], v[88:89], v[90:91]
	v_cvt_f32_ubyte3_e32 v91, v197
	v_cvt_f32_ubyte2_e32 v90, v197
	v_pk_mul_f32 v[90:91], v[90:91], s[62:63] op_sel_hi:[1,0]
	s_nop 0
	v_pk_mul_f32 v[84:85], v[84:85], v[90:91]
	s_cbranch_vccnz .LBB0_1199
	v_mov_b32_e32 v167, v1
	v_lshl_add_u64 v[90:91], v[100:101], 0, v[166:167]
	s_mov_b64 s[30:31], 0
	global_store_dwordx4 v[90:91], v[86:89], off offset:512
	global_store_dwordx4 v[90:91], v[82:85], off offset:528

;     __device__ __forceinline__ void operator()(const Acc& acc, const Unit& u, int wr, int wc, int fr, int fq) const {
;     ...
;                 u32x2 gw[2][2]; u32x4 ps[2][2];
; #pragma unroll
;                 for (int mm = 0; mm < 2; ++mm)
; #pragma unroll
;                     for (int bj = 0; bj < 2; ++bj) {
;                         const int row = row0 + ai * 128 + (2 * mh + mm) * 16, col = u.pn * 256 + bj * 128 + wc * 32 + 8 * fq;
;                         gw[mm][bj] = *(const u32x2*)((const unsigned char*)gates + (size_t)row * NGATE + br * 2048 + col);
;                         if (br > 0 && pcs == 0) ps[mm][bj] = scr[soff + (mm * 2 + bj) * 512];
;                     }
.LBB0_1206:
	v_add_u32_e32 v90, 0x80, v170
	v_mov_b64_e32 v[82:83], s[52:53]
	v_add_u32_e32 v0, 0x800, v0
	v_mad_i64_i32 v[82:83], s[30:31], v90, s63, v[82:83]
	v_lshl_add_u64 v[82:83], v[82:83], 0, v[160:161]
	s_nop 0
	s_and_b64 vcc, exec, s[46:47]
	s_cbranch_vccnz .LBB0_1208
	v_lshl_add_u64 v[78:79], v[0:1], 4, s[4:5]
	global_load_dwordx4 v[78:81], v[78:79], off

;     __device__ __forceinline__ void operator()(const Acc& acc, const Unit& u, int wr, int wc, int fr, int fq) const {
;     ...
;                 u32x2 gw[2][2]; u32x4 ps[2][2];
; #pragma unroll
;                 for (int mm = 0; mm < 2; ++mm)
; #pragma unroll
;                     for (int bj = 0; bj < 2; ++bj) {
;                         const int row = row0 + ai * 128 + (2 * mh + mm) * 16, col = u.pn * 256 + bj * 128 + wc * 32 + 8 * fq;
;                         gw[mm][bj] = *(const u32x2*)((const unsigned char*)gates + (size_t)row * NGATE + br * 2048 + col);
;                         if (br > 0 && pcs == 0) ps[mm][bj] = scr[soff + (mm * 2 + bj) * 512];
;                     }
.LBB0_1210:
	v_add_u32_e32 v86, 0x90, v170
	v_mov_b64_e32 v[82:83], s[52:53]
	v_mad_i64_i32 v[82:83], s[30:31], v86, s63, v[82:83]
	v_lshl_add_u64 v[82:83], v[82:83], 0, v[160:161]
	s_nop 0
	s_and_b64 vcc, exec, s[46:47]
	v_add_u32_e32 v84, 0x400, v0
	s_cbranch_vccnz .LBB0_1212
	v_mov_b32_e32 v85, v1
	v_lshl_add_u64 v[54:55], v[84:85], 4, s[4:5]
	global_load_dwordx4 v[54:57], v[54:55], off

;     __device__ __forceinline__ void operator()(const Acc& acc, const Unit& u, int wr, int wc, int fr, int fq) const {
;     ...
;                         const u32x2 g_ = gw[mm][bj]; const float k255 = 1.0f / 255.0f;
;                         f32x4 v0 = acc[ai][bj][m][0], v1 = acc[ai][bj][m][1];
; #pragma unroll
;                         for (int j = 0; j < 4; ++j) { v0[j] *= (float)((g_.x >> (8 * j)) & 0xffu) * k255; v1[j] *= (float)((g_.y >> (8 * j)) & 0xffu) * k255; }
;                         if (pcs) { float* d = pbase + (size_t)(wr * 64 + fr + ai * 128 + m * 16) * 256 + colt; *(f32x4*)d = v0; *(f32x4*)(d + 4) = v1; }
.LBB0_1214:
	s_waitcnt vmcnt(3)
	v_cvt_f32_ubyte1_e32 v99, v198
	v_cvt_f32_ubyte0_e32 v98, v198
	v_pk_mul_f32 v[98:99], v[98:99], s[62:63] op_sel_hi:[1,0]
	v_lshlrev_b64 v[94:95], 10, v[168:169]
	v_pk_mul_f32 v[74:75], v[74:75], v[98:99]
	v_cvt_f32_ubyte1_e32 v99, v199
	v_cvt_f32_ubyte0_e32 v98, v199
	v_pk_mul_f32 v[98:99], v[98:99], s[62:63] op_sel_hi:[1,0]
	v_lshl_add_u64 v[94:95], s[50:51], 0, v[94:95]
	v_pk_mul_f32 v[70:71], v[70:71], v[98:99]
	v_cvt_f32_ubyte3_e32 v99, v198
	v_cvt_f32_ubyte2_e32 v98, v198
	v_pk_mul_f32 v[98:99], v[98:99], s[62:63] op_sel_hi:[1,0]
	s_mov_b64 s[30:31], 0x20000
	v_pk_mul_f32 v[76:77], v[76:77], v[98:99]
	v_cvt_f32_ubyte3_e32 v99, v199
	v_cvt_f32_ubyte2_e32 v98, v199
	v_pk_mul_f32 v[96:97], v[98:99], s[62:63] op_sel_hi:[1,0]
	v_lshl_add_u64 v[94:95], v[94:95], 0, s[30:31]
	v_pk_mul_f32 v[72:73], v[72:73], v[96:97]
	s_and_b64 vcc, exec, s[42:43]
	s_mov_b64 s[30:31], -1
	s_cbranch_vccnz .LBB0_1216
	v_mov_b32_e32 v167, v1
	v_lshl_add_u64 v[96:97], v[94:95], 0, v[166:167]
	s_mov_b64 s[30:31], 0
	global_store_dwordx4 v[96:97], v[74:77], off
	global_store_dwordx4 v[96:97], v[70:73], off offset:16

;     __device__ __forceinline__ void operator()(const Acc& acc, const Unit& u, int wr, int wc, int fr, int fq) const {
;     ...
;                         const u32x2 g_ = gw[mm][bj]; const float k255 = 1.0f / 255.0f;
;                         f32x4 v0 = acc[ai][bj][m][0], v1 = acc[ai][bj][m][1];
; #pragma unroll
;                         for (int j = 0; j < 4; ++j) { v0[j] *= (float)((g_.x >> (8 * j)) & 0xffu) * k255; v1[j] *= (float)((g_.y >> (8 * j)) & 0xffu) * k255; }
;                         if (pcs) { float* d = pbase + (size_t)(wr * 64 + fr + ai * 128 + m * 16) * 256 + colt; *(f32x4*)d = v0; *(f32x4*)(d + 4) = v1; }
.LBB0_1223:
	s_waitcnt vmcnt(2)
	v_cvt_f32_ubyte1_e32 v71, v200
	v_cvt_f32_ubyte0_e32 v70, v200
	v_pk_mul_f32 v[70:71], v[70:71], s[62:63] op_sel_hi:[1,0]
	s_and_b64 vcc, exec, s[42:43]
	v_pk_mul_f32 v[62:63], v[62:63], v[70:71]
	v_cvt_f32_ubyte1_e32 v71, v201
	v_cvt_f32_ubyte0_e32 v70, v201
	v_pk_mul_f32 v[70:71], v[70:71], s[62:63] op_sel_hi:[1,0]
	s_mov_b64 s[30:31], -1
	v_pk_mul_f32 v[58:59], v[58:59], v[70:71]
	v_cvt_f32_ubyte3_e32 v71, v200
	v_cvt_f32_ubyte2_e32 v70, v200
	v_pk_mul_f32 v[70:71], v[70:71], s[62:63] op_sel_hi:[1,0]
	s_nop 0
	v_pk_mul_f32 v[64:65], v[64:65], v[70:71]
	v_cvt_f32_ubyte3_e32 v71, v201
	v_cvt_f32_ubyte2_e32 v70, v201
	v_pk_mul_f32 v[70:71], v[70:71], s[62:63] op_sel_hi:[1,0]
	s_nop 0
	v_pk_mul_f32 v[60:61], v[60:61], v[70:71]
	s_cbranch_vccnz .LBB0_1225
	v_mov_b32_e32 v167, v1
	v_lshl_add_u64 v[70:71], v[94:95], 0, v[166:167]
	s_mov_b64 s[30:31], 0
	global_store_dwordx4 v[70:71], v[62:65], off offset:512
	global_store_dwordx4 v[70:71], v[58:61], off offset:528

;     __device__ __forceinline__ void operator()(const Acc& acc, const Unit& u, int wr, int wc, int fr, int fq) const {
;     ...
;                         const int m = 2 * mh + mm; const int row = row0 + ai * 128 + m * 16; const int colt = bj * 128 + wc * 32 + 8 * fq, col = u.pn * 256 + colt;
;                         const u32x2 g_ = gw[mm][bj]; const float k255 = 1.0f / 255.0f;
;                         f32x4 v0 = acc[ai][bj][m][0], v1 = acc[ai][bj][m][1];
; #pragma unroll
;                         for (int j = 0; j < 4; ++j) { v0[j] *= (float)((g_.x >> (8 * j)) & 0xffu) * k255; v1[j] *= (float)((g_.y >> (8 * j)) & 0xffu) * k255; }
;                         if (pcs) { float* d = pbase + (size_t)(wr * 64 + fr + ai * 128 + m * 16) * 256 + colt; *(f32x4*)d = v0; *(f32x4*)(d + 4) = v1; }
.LBB0_1232:
	v_lshlrev_b64 v[58:59], 10, v[168:169]
	v_lshl_add_u64 v[58:59], s[50:51], 0, v[58:59]
	s_mov_b64 s[30:31], 0x24000
	v_lshl_add_u64 v[60:61], v[58:59], 0, s[30:31]
	s_waitcnt vmcnt(1)
	v_cvt_f32_ubyte1_e32 v59, v202
	v_cvt_f32_ubyte0_e32 v58, v202
	v_pk_mul_f32 v[58:59], v[58:59], s[62:63] op_sel_hi:[1,0]
	s_and_b64 vcc, exec, s[42:43]
	v_pk_mul_f32 v[50:51], v[50:51], v[58:59]
	v_cvt_f32_ubyte1_e32 v59, v203
	v_cvt_f32_ubyte0_e32 v58, v203
	v_pk_mul_f32 v[58:59], v[58:59], s[62:63] op_sel_hi:[1,0]
	s_mov_b64 s[30:31], -1
	v_pk_mul_f32 v[46:47], v[46:47], v[58:59]
	v_cvt_f32_ubyte3_e32 v59, v202
	v_cvt_f32_ubyte2_e32 v58, v202
	v_pk_mul_f32 v[58:59], v[58:59], s[62:63] op_sel_hi:[1,0]
	s_nop 0
	v_pk_mul_f32 v[52:53], v[52:53], v[58:59]
	v_cvt_f32_ubyte3_e32 v59, v203
	v_cvt_f32_ubyte2_e32 v58, v203
	v_pk_mul_f32 v[58:59], v[58:59], s[62:63] op_sel_hi:[1,0]
	s_nop 0
	v_pk_mul_f32 v[48:49], v[48:49], v[58:59]
	s_cbranch_vccnz .LBB0_1234
	v_mov_b32_e32 v167, v1
	v_lshl_add_u64 v[58:59], v[60:61], 0, v[166:167]
	s_mov_b64 s[30:31], 0
	global_store_dwordx4 v[58:59], v[50:53], off
	global_store_dwordx4 v[58:59], v[46:49], off offset:16

;     __device__ __forceinline__ void operator()(const Acc& acc, const Unit& u, int wr, int wc, int fr, int fq) const {
;     ...
;                         const u32x2 g_ = gw[mm][bj]; const float k255 = 1.0f / 255.0f;
;                         f32x4 v0 = acc[ai][bj][m][0], v1 = acc[ai][bj][m][1];
; #pragma unroll
;                         for (int j = 0; j < 4; ++j) { v0[j] *= (float)((g_.x >> (8 * j)) & 0xffu) * k255; v1[j] *= (float)((g_.y >> (8 * j)) & 0xffu) * k255; }
;                         if (pcs) { float* d = pbase + (size_t)(wr * 64 + fr + ai * 128 + m * 16) * 256 + colt; *(f32x4*)d = v0; *(f32x4*)(d + 4) = v1; }
.LBB0_1241:
	s_waitcnt vmcnt(0)
	v_cvt_f32_ubyte1_e32 v47, v204
	v_cvt_f32_ubyte0_e32 v46, v204
	v_pk_mul_f32 v[46:47], v[46:47], s[62:63] op_sel_hi:[1,0]
	s_and_b64 vcc, exec, s[42:43]
	v_pk_mul_f32 v[38:39], v[38:39], v[46:47]
	v_cvt_f32_ubyte1_e32 v47, v205
	v_cvt_f32_ubyte0_e32 v46, v205
	v_pk_mul_f32 v[46:47], v[46:47], s[62:63] op_sel_hi:[1,0]
	s_mov_b64 s[30:31], -1
	v_pk_mul_f32 v[34:35], v[34:35], v[46:47]
	v_cvt_f32_ubyte3_e32 v47, v204
	v_cvt_f32_ubyte2_e32 v46, v204
	v_pk_mul_f32 v[46:47], v[46:47], s[62:63] op_sel_hi:[1,0]
	s_nop 0
	v_pk_mul_f32 v[40:41], v[40:41], v[46:47]
	v_cvt_f32_ubyte3_e32 v47, v205
	v_cvt_f32_ubyte2_e32 v46, v205
	v_pk_mul_f32 v[46:47], v[46:47], s[62:63] op_sel_hi:[1,0]
	s_nop 0
	v_pk_mul_f32 v[36:37], v[36:37], v[46:47]
	s_cbranch_vccnz .LBB0_1243
	v_mov_b32_e32 v167, v1
	v_lshl_add_u64 v[46:47], v[60:61], 0, v[166:167]
	s_mov_b64 s[30:31], 0
	global_store_dwordx4 v[46:47], v[38:41], off offset:512
	global_store_dwordx4 v[46:47], v[34:37], off offset:528

;     __device__ __forceinline__ void operator()(const Acc& acc, const Unit& u, int wr, int wc, int fr, int fq) const {
;     ...
;                 u32x2 gw[2][2]; u32x4 ps[2][2];
; #pragma unroll
;                 for (int mm = 0; mm < 2; ++mm)
; #pragma unroll
;                     for (int bj = 0; bj < 2; ++bj) {
;                         const int row = row0 + ai * 128 + (2 * mh + mm) * 16, col = u.pn * 256 + bj * 128 + wc * 32 + 8 * fq;
;                         gw[mm][bj] = *(const u32x2*)((const unsigned char*)gates + (size_t)row * NGATE + br * 2048 + col);
;                         if (br > 0 && pcs == 0) ps[mm][bj] = scr[soff + (mm * 2 + bj) * 512];
;                     }
.LBB0_1250:
	v_add_u32_e32 v46, 0xa0, v170
	v_mov_b64_e32 v[34:35], s[52:53]
	v_add_u32_e32 v0, 0x800, v0
	v_mad_i64_i32 v[34:35], s[30:31], v46, s63, v[34:35]
	v_lshl_add_u64 v[34:35], v[34:35], 0, v[160:161]
	s_nop 0
	s_and_b64 vcc, exec, s[46:47]
	s_cbranch_vccnz .LBB0_1252
	v_lshl_add_u64 v[36:37], v[0:1], 4, s[4:5]
	global_load_dwordx4 v[78:81], v[36:37], off
.LBB0_1252:
	s_nop 0
	s_and_b64 vcc, exec, s[46:47]
	s_cbranch_vccnz .LBB0_1254
	v_add_u32_e32 v34, 0x200, v0
	v_mov_b32_e32 v35, v1
	v_lshl_add_u64 v[34:35], v[34:35], 4, s[4:5]
	global_load_dwordx4 v[66:69], v[34:35], off
.LBB0_1254:
	v_add_u32_e32 v38, 0xb0, v170
	v_mov_b64_e32 v[34:35], s[52:53]
	v_mad_i64_i32 v[34:35], s[30:31], v38, s63, v[34:35]
	v_lshl_add_u64 v[34:35], v[34:35], 0, v[160:161]
	s_nop 0
	s_and_b64 vcc, exec, s[46:47]
	v_add_u32_e32 v36, 0x400, v0
	s_cbranch_vccnz .LBB0_1256
	v_mov_b32_e32 v37, v1
	v_lshl_add_u64 v[50:51], v[36:37], 4, s[4:5]
	global_load_dwordx4 v[54:57], v[50:51], off

;     __device__ __forceinline__ void operator()(const Acc& acc, const Unit& u, int wr, int wc, int fr, int fq) const {
;     ...
;                         const u32x2 g_ = gw[mm][bj]; const float k255 = 1.0f / 255.0f;
;                         f32x4 v0 = acc[ai][bj][m][0], v1 = acc[ai][bj][m][1];
; #pragma unroll
;                         for (int j = 0; j < 4; ++j) { v0[j] *= (float)((g_.x >> (8 * j)) & 0xffu) * k255; v1[j] *= (float)((g_.y >> (8 * j)) & 0xffu) * k255; }
;                         if (pcs) { float* d = pbase + (size_t)(wr * 64 + fr + ai * 128 + m * 16) * 256 + colt; *(f32x4*)d = v0; *(f32x4*)(d + 4) = v1; }
.LBB0_1258:
	s_waitcnt vmcnt(3)
	v_cvt_f32_ubyte1_e32 v59, v224
	v_cvt_f32_ubyte0_e32 v58, v224
	v_pk_mul_f32 v[58:59], v[58:59], s[62:63] op_sel_hi:[1,0]
	v_lshlrev_b64 v[50:51], 10, v[168:169]
	v_pk_mul_f32 v[30:31], v[30:31], v[58:59]
	v_cvt_f32_ubyte1_e32 v59, v225
	v_cvt_f32_ubyte0_e32 v58, v225
	v_pk_mul_f32 v[58:59], v[58:59], s[62:63] op_sel_hi:[1,0]
	v_lshl_add_u64 v[50:51], s[50:51], 0, v[50:51]
	v_pk_mul_f32 v[26:27], v[26:27], v[58:59]
	v_cvt_f32_ubyte3_e32 v59, v224
	v_cvt_f32_ubyte2_e32 v58, v224
	v_pk_mul_f32 v[58:59], v[58:59], s[62:63] op_sel_hi:[1,0]
	v_lshl_add_u64 v[50:51], v[50:51], 0, s[38:39]
	v_pk_mul_f32 v[32:33], v[32:33], v[58:59]
	v_cvt_f32_ubyte3_e32 v59, v225
	v_cvt_f32_ubyte2_e32 v58, v225
	v_pk_mul_f32 v[52:53], v[58:59], s[62:63] op_sel_hi:[1,0]
	s_and_b64 vcc, exec, s[42:43]
	v_pk_mul_f32 v[28:29], v[28:29], v[52:53]
	s_mov_b64 s[30:31], -1
	s_cbranch_vccnz .LBB0_1260
	v_mov_b32_e32 v167, v1
	v_lshl_add_u64 v[52:53], v[50:51], 0, v[166:167]
	s_mov_b64 s[30:31], 0
	global_store_dwordx4 v[52:53], v[30:33], off
	global_store_dwordx4 v[52:53], v[26:29], off offset:16

;     __device__ __forceinline__ void operator()(const Acc& acc, const Unit& u, int wr, int wc, int fr, int fq) const {
;     ...
;                         const u32x2 g_ = gw[mm][bj]; const float k255 = 1.0f / 255.0f;
;                         f32x4 v0 = acc[ai][bj][m][0], v1 = acc[ai][bj][m][1];
; #pragma unroll
;                         for (int j = 0; j < 4; ++j) { v0[j] *= (float)((g_.x >> (8 * j)) & 0xffu) * k255; v1[j] *= (float)((g_.y >> (8 * j)) & 0xffu) * k255; }
;                         if (pcs) { float* d = pbase + (size_t)(wr * 64 + fr + ai * 128 + m * 16) * 256 + colt; *(f32x4*)d = v0; *(f32x4*)(d + 4) = v1; }
.LBB0_1267:
	s_waitcnt vmcnt(2)
	v_cvt_f32_ubyte1_e32 v27, v226
	v_cvt_f32_ubyte0_e32 v26, v226
	v_pk_mul_f32 v[26:27], v[26:27], s[62:63] op_sel_hi:[1,0]
	s_and_b64 vcc, exec, s[42:43]
	v_pk_mul_f32 v[22:23], v[22:23], v[26:27]
	v_cvt_f32_ubyte1_e32 v27, v227
	v_cvt_f32_ubyte0_e32 v26, v227
	v_pk_mul_f32 v[26:27], v[26:27], s[62:63] op_sel_hi:[1,0]
	s_mov_b64 s[30:31], -1
	v_pk_mul_f32 v[18:19], v[18:19], v[26:27]
	v_cvt_f32_ubyte3_e32 v27, v226
	v_cvt_f32_ubyte2_e32 v26, v226
	v_pk_mul_f32 v[26:27], v[26:27], s[62:63] op_sel_hi:[1,0]
	s_nop 0
	v_pk_mul_f32 v[24:25], v[24:25], v[26:27]
	v_cvt_f32_ubyte3_e32 v27, v227
	v_cvt_f32_ubyte2_e32 v26, v227
	v_pk_mul_f32 v[26:27], v[26:27], s[62:63] op_sel_hi:[1,0]
	s_nop 0
	v_pk_mul_f32 v[20:21], v[20:21], v[26:27]
	s_cbranch_vccnz .LBB0_1269
	v_mov_b32_e32 v167, v1
	v_lshl_add_u64 v[26:27], v[50:51], 0, v[166:167]
	s_mov_b64 s[30:31], 0
	global_store_dwordx4 v[26:27], v[22:25], off offset:512
	global_store_dwordx4 v[26:27], v[18:21], off offset:528

;     __device__ __forceinline__ void operator()(const Acc& acc, const Unit& u, int wr, int wc, int fr, int fq) const {
;     ...
;                         const int m = 2 * mh + mm; const int row = row0 + ai * 128 + m * 16; const int colt = bj * 128 + wc * 32 + 8 * fq, col = u.pn * 256 + colt;
;                         const u32x2 g_ = gw[mm][bj]; const float k255 = 1.0f / 255.0f;
;                         f32x4 v0 = acc[ai][bj][m][0], v1 = acc[ai][bj][m][1];
; #pragma unroll
;                         for (int j = 0; j < 4; ++j) { v0[j] *= (float)((g_.x >> (8 * j)) & 0xffu) * k255; v1[j] *= (float)((g_.y >> (8 * j)) & 0xffu) * k255; }
;                         if (pcs) { float* d = pbase + (size_t)(wr * 64 + fr + ai * 128 + m * 16) * 256 + colt; *(f32x4*)d = v0; *(f32x4*)(d + 4) = v1; }
.LBB0_1276:
	v_lshlrev_b64 v[18:19], 10, v[168:169]
	v_lshl_add_u64 v[18:19], s[50:51], 0, v[18:19]
	s_mov_b64 s[30:31], 0x2c000
	v_lshl_add_u64 v[20:21], v[18:19], 0, s[30:31]
	s_waitcnt vmcnt(1)
	v_cvt_f32_ubyte1_e32 v19, v244
	v_cvt_f32_ubyte0_e32 v18, v244
	v_pk_mul_f32 v[18:19], v[18:19], s[62:63] op_sel_hi:[1,0]
	s_and_b64 vcc, exec, s[42:43]
	v_pk_mul_f32 v[14:15], v[14:15], v[18:19]
	v_cvt_f32_ubyte1_e32 v19, v245
	v_cvt_f32_ubyte0_e32 v18, v245
	v_pk_mul_f32 v[18:19], v[18:19], s[62:63] op_sel_hi:[1,0]
	s_mov_b64 s[30:31], -1
	v_pk_mul_f32 v[10:11], v[10:11], v[18:19]
	v_cvt_f32_ubyte3_e32 v19, v244
	v_cvt_f32_ubyte2_e32 v18, v244
	v_pk_mul_f32 v[18:19], v[18:19], s[62:63] op_sel_hi:[1,0]
	s_nop 0
	v_pk_mul_f32 v[16:17], v[16:17], v[18:19]
	v_cvt_f32_ubyte3_e32 v19, v245
	v_cvt_f32_ubyte2_e32 v18, v245
	v_pk_mul_f32 v[18:19], v[18:19], s[62:63] op_sel_hi:[1,0]
	s_nop 0
	v_pk_mul_f32 v[12:13], v[12:13], v[18:19]
	s_cbranch_vccnz .LBB0_1278
	v_mov_b32_e32 v167, v1
	v_lshl_add_u64 v[18:19], v[20:21], 0, v[166:167]
	s_mov_b64 s[30:31], 0
	global_store_dwordx4 v[18:19], v[14:17], off
	global_store_dwordx4 v[18:19], v[10:13], off offset:16

;     __device__ __forceinline__ void operator()(const Acc& acc, const Unit& u, int wr, int wc, int fr, int fq) const {
;     ...
;                         const u32x2 g_ = gw[mm][bj]; const float k255 = 1.0f / 255.0f;
;                         f32x4 v0 = acc[ai][bj][m][0], v1 = acc[ai][bj][m][1];
; #pragma unroll
;                         for (int j = 0; j < 4; ++j) { v0[j] *= (float)((g_.x >> (8 * j)) & 0xffu) * k255; v1[j] *= (float)((g_.y >> (8 * j)) & 0xffu) * k255; }
;                         if (pcs) { float* d = pbase + (size_t)(wr * 64 + fr + ai * 128 + m * 16) * 256 + colt; *(f32x4*)d = v0; *(f32x4*)(d + 4) = v1; }
.LBB0_1285:
	s_waitcnt vmcnt(0)
	v_cvt_f32_ubyte1_e32 v11, v246
	v_cvt_f32_ubyte0_e32 v10, v246
	v_pk_mul_f32 v[10:11], v[10:11], s[62:63] op_sel_hi:[1,0]
	s_and_b64 vcc, exec, s[42:43]
	v_pk_mul_f32 v[6:7], v[6:7], v[10:11]
	v_cvt_f32_ubyte1_e32 v11, v247
	v_cvt_f32_ubyte0_e32 v10, v247
	v_pk_mul_f32 v[10:11], v[10:11], s[62:63] op_sel_hi:[1,0]
	s_mov_b64 s[30:31], -1
	v_pk_mul_f32 v[2:3], v[2:3], v[10:11]
	v_cvt_f32_ubyte3_e32 v11, v246
	v_cvt_f32_ubyte2_e32 v10, v246
	v_pk_mul_f32 v[10:11], v[10:11], s[62:63] op_sel_hi:[1,0]
	s_nop 0
	v_pk_mul_f32 v[8:9], v[8:9], v[10:11]
	v_cvt_f32_ubyte3_e32 v11, v247
	v_cvt_f32_ubyte2_e32 v10, v247
	v_pk_mul_f32 v[10:11], v[10:11], s[62:63] op_sel_hi:[1,0]
	s_nop 0
	v_pk_mul_f32 v[4:5], v[4:5], v[10:11]
	s_cbranch_vccnz .LBB0_1287
	v_mov_b32_e32 v167, v1
	v_lshl_add_u64 v[10:11], v[20:21], 0, v[166:167]
	s_mov_b64 s[30:31], 0
	global_store_dwordx4 v[10:11], v[6:9], off offset:512
	global_store_dwordx4 v[10:11], v[2:5], off offset:528
